# scan: Y rows written back by the helper waves as well
# baseline (speedup 1.0000x reference)
; #define otid() otid_(wid_k)
; DI void scan_block(float* ldsf, const u16* __restrict__ R, const u16* __restrict__ KP, const u16* __restrict__ KK, const u16* __restrict__ KKA,
;                    const u16* __restrict__ V, const float* __restrict__ Wd, float* __restrict__ Y, int blk, int wid_k) {
;   const int tid = otid(), lane = tid & 63, w = tid >> 6;
;   const int bh = blk >> 2, rq = blk & 3, b = bh >> 2, h = bh & 3;
;   const int ks = lane & 15, rowl = (w & 3) * 4 + (lane >> 4);
;   const bool worker = (w < 4);
;   float* ybuf = ldsf + 2 * 16 * 336;
;   float S0 = 0.f, S1 = 0.f, S2 = 0.f, S3 = 0.f, yreg = 0.f;
;   const size_t tb = (size_t)b * SEQ;
;   const int hc = h * 64;
;   const int a0i = tid >> 7, a0step = (tid & 127) >> 3, a0c = (tid & 7) * 8;
;   const int wstep = (tid & 255) >> 4, wc = (tid & 15) * 4;
;   const int vstep = (tid & 31) >> 1, vhalf = tid & 1;
;     ...
;     if (tid < 256) {
;       const int step = tid >> 4, row = tid & 15;
;       Y[(tb + (size_t)c * 16 + step) * 256 + hc + rq * 16 + row] = yb[tid];
;     }
.LBB0_1280:
	s_or_b64 exec, exec, s[6:7]
	v_lshrrev_b32_e32 v15, 4, v69
	v_ashrrev_i32_e32 v22, 6, v69
	v_lshlrev_b32_e32 v23, 2, v22
	v_and_b32_e32 v15, 3, v15
	v_cmp_gt_i32_e64 s[6:7], 4, v22
	v_ashrrev_i32_e32 v22, 4, v69
	s_lshl_b64 s[64:65], s[60:61], 22
	v_and_or_b32 v24, v23, 12, v15
	v_ashrrev_i32_e32 v23, 31, v22
	s_add_u32 s66, s64, 0x88a0000
	s_addc_u32 s67, s65, 0
	v_lshlrev_b64 v[22:23], 10, v[22:23]
	v_lshl_add_u64 v[56:57], s[66:67], 0, v[22:23]
	s_lshl_b32 s66, s63, 6
	s_and_b32 s66, s66, 0x300
	s_and_b32 s67, s63, 3
	v_or_b32_e32 v15, s66, v56
	s_lshl_b32 s68, s67, 6
	s_lshl_b64 s[60:61], s[60:61], 21
	s_lshl_b32 s63, s63, 5
	v_or3_b32 v56, v15, s68, v70
	v_mov_b32_e32 v98, 0x4000
	v_cmp_lt_u32_e32 vcc, 0xff, v69
	s_nop 1
	v_cndmask_b32_e32 v98, 0, v98, vcc
	v_sub_co_u32_e32 v56, vcc, v56, v98
	s_nop 1
	v_subbrev_co_u32_e32 v57, vcc, 0, v57, vcc
	v_lshl_or_b32 v15, v21, 9, s60
	s_and_b32 s72, s63, 0x180
	v_or_b32_e32 v15, s72, v15
	s_lshl_b32 s63, s67, 5
	v_or3_b32 v58, v15, s63, v14
	v_lshl_or_b32 v14, v19, 10, s64
	v_lshlrev_b32_e32 v15, 4, v18
	v_or3_b32 v60, v14, s66, v15
	v_lshl_add_u64 v[14:15], v[0:1], 0, s[60:61]
	v_lshlrev_b32_e32 v0, 9, v17
	v_lshl_add_u64 v[14:15], v[14:15], 0, v[0:1]
	v_and_b32_e32 v0, 7, v16
	v_lshl_add_u64 v[14:15], v[14:15], 0, s[72:73]
	v_lshlrev_b32_e32 v0, 4, v0
	v_lshlrev_b32_e32 v20, 6, v20
	v_lshl_add_u64 v[62:63], v[14:15], 0, v[0:1]
	v_mov_b32_e32 v14, 0
	v_cmp_eq_u32_e64 s[8:9], 15, v18
	v_lshlrev_b32_e32 v75, 6, v18
	s_mov_b32 s62, 0
	v_cmp_eq_u32_e64 s[10:11], 0, v18
	v_cmp_eq_u32_e64 s[12:13], 1, v18
	v_cmp_eq_u32_e64 s[14:15], 2, v18
	v_cmp_eq_u32_e64 s[16:17], 3, v18
	v_cmp_eq_u32_e64 s[18:19], 4, v18
	v_cmp_eq_u32_e64 s[20:21], 5, v18
	v_cmp_eq_u32_e64 s[22:23], 6, v18
	v_cmp_eq_u32_e64 s[24:25], 7, v18
	v_cmp_eq_u32_e64 s[26:27], 8, v18
	v_cmp_eq_u32_e64 s[28:29], 9, v18
	v_cmp_eq_u32_e64 s[30:31], 10, v18
	v_cmp_eq_u32_e64 s[34:35], 11, v18
	v_cmp_eq_u32_e64 s[36:37], 12, v18
	v_cmp_eq_u32_e64 s[38:39], 13, v18
	v_cmp_eq_u32_e64 s[40:41], 14, v18
	v_mov_b32_e32 v59, s61
	v_mov_b32_e32 v61, s65
	v_lshlrev_b32_e32 v76, 2, v24
	v_lshlrev_b32_e32 v77, 2, v20
	v_mov_b32_e32 v15, v14
	v_mov_b32_e32 v16, v14
	v_mov_b32_e32 v17, v14
	v_mov_b32_e32 v0, v14
	s_waitcnt lgkmcnt(0)
	s_barrier
	s_branch .LBB0_1282

; DI void scan_block(float* ldsf, const u16* __restrict__ R, const u16* __restrict__ KP, const u16* __restrict__ KK, const u16* __restrict__ KKA,
;                    const u16* __restrict__ V, const float* __restrict__ Wd, float* __restrict__ Y, int blk, int wid_k) {
;     ...
;     __syncthreads();
;     if (tid < 256) {
;       const int step = tid >> 4, row = tid & 15;
;       Y[(tb + (size_t)c * 16 + step) * 256 + hc + rq * 16 + row] = yb[tid];
;     }
.LBB0_1296:
	s_waitcnt lgkmcnt(0)
	s_barrier
	s_andn1_saveexec_b64 s[60:61], s[2:3]
	s_cbranch_execz .LBB0_1281
	v_lshl_add_u32 v18, v69, 2, s63
	ds_read_b32 v20, v18 offset:41984
	v_lshl_add_u64 v[18:19], s[48:49], 0, v[56:57]
	s_waitcnt lgkmcnt(0)
	global_store_dword v[18:19], v20, off
	s_branch .LBB0_1281
